# GEMM K-loops: 25 more m0-write hazard s_nops replaced by independent scalar instructions hoisted from later in the loop body (dependency-checked), 3 stale pads dropped
# baseline (speedup 1.0000x reference)
; #define PG8_STAGE(bufoff, gbase, voff) do { unsigned long long _gb = (unsigned long long)(gbase); asm volatile("" : "+s"(_gb)); _Pragma("unroll") for (int _i = 0; _i < 2; ++_i) \
;         __builtin_amdgcn_global_load_lds((const GAS unsigned*)((const GAS char*)_gb + (voff)[_i]), (LAS unsigned*)(lds + (bufoff) + ldsw + _i * 8192), 16, 0, 0); } while (0)
; #define PG8_LDA(dst, b, h) do { _Pragma("unroll") for (int m = 0; m < 4; ++m) _Pragma("unroll") for (int k = 0; k < 2; ++k) dst[m][k] = *(const LAS bf16x8*)(lds + PG8_SA(b, h) + aoff + m * 2048 + k * 1024); } while (0)
; #define PG8_LDB(dst, b, h) do { _Pragma("unroll") for (int n = 0; n < 2; ++n) _Pragma("unroll") for (int k = 0; k < 2; ++k) dst[n][k] = *(const LAS bf16x8*)(lds + PG8_SB(b, h) + boff + n * 2048 + k * 1024); } while (0)
; #define PG8_WAIT_V(n) asm volatile("s_waitcnt vmcnt(" #n ")" ::: "memory")
; #define PG8_BAR __builtin_amdgcn_s_barrier()
; template <class Epi, bool ALIGN_EPI>
; __device__ __forceinline__ void gemm_phase(LAS unsigned char* lds, const Gemm g, const StaticOrder& S, const Epi& E, const int wid) {
;     ...
;         const char* nA = has_next ? (const char*)g.A + (size_t)nxt.pm * tstep : cA; const char* nB = has_next ? (const char*)g.Bt + (size_t)nxt.pn * tstep : cB;
;         for (int t = 0; t < nt; t += 2) {
;             const bool last = (t == nt - 2);
;             const char* a1 = cA + (size_t)(t + 1) * kstep;
;             const char* a2 = last ? nA : cA + (size_t)(t + 2) * kstep; const char* b2 = last ? nB : cB + (size_t)(t + 2) * kstep;
;             const char* a3 = a2 + kstep; const char* b3 = b2 + kstep;
;             PG8_LDB(B0, 0, 0); PG8_LDB(B1, 0, 1); PG8_SCHED; PG8_LDA(At, 0, 0); PG8_STAGE(PG8_SA(1, 1), a1 + hstep, voffA);
;             PG8_WAIT_V(8); PG8_WAIT_L(0); PG8_BAR; PG8_MMA(0, 0, At, B0); PG8_MMA(0, 1, At, B1); PG8_BAR; PG8_SCHED;
;             PG8_LDA(At, 0, 1); PG8_STAGE(PG8_SB(0, 0), b2, voffB); PG8_STAGE(PG8_SB(0, 1), b2 + hstepB, voffB); PG8_STAGE(PG8_SA(0, 0), a2, voffA);
;             PG8_WAIT_V(8); PG8_WAIT_L(0); PG8_BAR; PG8_MMA(1, 0, At, B0); PG8_MMA(1, 1, At, B1); PG8_BAR; PG8_SCHED;
;             PG8_LDB(B0, 1, 0); PG8_LDB(B1, 1, 1); PG8_SCHED; PG8_LDA(At, 1, 0); PG8_STAGE(PG8_SA(0, 1), a2 + hstep, voffA);
;             PG8_WAIT_V(8); PG8_WAIT_L(0); PG8_BAR; PG8_MMA(0, 0, At, B0); PG8_MMA(0, 1, At, B1); PG8_BAR; PG8_SCHED;
.LBB0_105:
	ds_read_b128 v[128:131], v204
	ds_read_b128 v[132:135], v204 offset:1024
	ds_read_b128 v[136:139], v204 offset:2048
	ds_read_b128 v[140:143], v204 offset:3072
	ds_read_b128 v[162:165], v205
	ds_read_b128 v[166:169], v205 offset:1024
	ds_read_b128 v[170:173], v205 offset:2048
	ds_read_b128 v[174:177], v205 offset:3072
	s_add_u32 s6, s2, 0x100
	s_addc_u32 s7, s3, 0
	s_cmp_eq_u32 s74, 28
	s_cselect_b32 s52, s70, s6
	s_cselect_b32 s53, s39, s7
	s_cselect_b32 s50, s71, s72
	s_cselect_b32 s51, s37, s73
	s_add_u32 s48, s52, 0x80
	s_addc_u32 s49, s53, 0
	s_add_u32 s2, s2, 0x80080
	s_addc_u32 s3, s3, 0
	ds_read_b128 v[178:181], v206
	ds_read_b128 v[186:189], v206 offset:1024
	ds_read_b128 v[190:193], v206 offset:2048
	ds_read_b128 v[194:197], v206 offset:3072
	ds_read_b128 v[198:201], v206 offset:4096
	ds_read_b128 v[210:213], v206 offset:5120
	ds_read_b128 v[214:217], v206 offset:6144
	s_add_i32 m0, s45, 0xc000
	ds_read_b128 v[218:221], v206 offset:7168
	global_load_lds_dwordx4 v144, s[2:3]
	s_add_i32 m0, s45, 0xe000
	s_add_i32 s75, s66, s33
	global_load_lds_dwordx4 v148, s[2:3]
	s_waitcnt vmcnt(8) lgkmcnt(0)
	s_barrier
	s_setprio 1
	v_mfma_f32_16x16x32_bf16 v[124:127], v[128:131], v[178:181], v[124:127]
	v_mfma_f32_16x16x32_bf16 v[120:123], v[136:139], v[178:181], v[120:123]
	v_mfma_f32_16x16x32_bf16 v[108:111], v[128:131], v[190:193], v[108:111]
	v_mfma_f32_16x16x32_bf16 v[104:107], v[136:139], v[190:193], v[104:107]
	v_mfma_f32_16x16x32_bf16 v[92:95], v[128:131], v[198:201], v[92:95]
	v_mfma_f32_16x16x32_bf16 v[88:91], v[136:139], v[198:201], v[88:91]
	v_mfma_f32_16x16x32_bf16 v[76:79], v[128:131], v[214:217], v[76:79]
	v_mfma_f32_16x16x32_bf16 v[72:75], v[136:139], v[214:217], v[72:75]
	v_mfma_f32_16x16x32_bf16 v[124:127], v[132:135], v[186:189], v[124:127]
	v_mfma_f32_16x16x32_bf16 v[120:123], v[140:143], v[186:189], v[120:123]
	v_mfma_f32_16x16x32_bf16 v[108:111], v[132:135], v[194:197], v[108:111]
	v_mfma_f32_16x16x32_bf16 v[104:107], v[140:143], v[194:197], v[104:107]
	v_mfma_f32_16x16x32_bf16 v[92:95], v[132:135], v[210:213], v[92:95]
	v_mfma_f32_16x16x32_bf16 v[88:91], v[140:143], v[210:213], v[88:91]
	v_mfma_f32_16x16x32_bf16 v[76:79], v[132:135], v[218:221], v[76:79]
	v_mfma_f32_16x16x32_bf16 v[72:75], v[140:143], v[218:221], v[72:75]
	v_mfma_f32_16x16x32_bf16 v[116:119], v[162:165], v[178:181], v[116:119]
	v_mfma_f32_16x16x32_bf16 v[112:115], v[170:173], v[178:181], v[112:115]
	v_mfma_f32_16x16x32_bf16 v[100:103], v[162:165], v[190:193], v[100:103]
	v_mfma_f32_16x16x32_bf16 v[96:99], v[170:173], v[190:193], v[96:99]
	v_mfma_f32_16x16x32_bf16 v[84:87], v[162:165], v[198:201], v[84:87]
	v_mfma_f32_16x16x32_bf16 v[80:83], v[170:173], v[198:201], v[80:83]
	v_mfma_f32_16x16x32_bf16 v[68:71], v[162:165], v[214:217], v[68:71]
	v_mfma_f32_16x16x32_bf16 v[64:67], v[170:173], v[214:217], v[64:67]
	v_mfma_f32_16x16x32_bf16 v[116:119], v[166:169], v[186:189], v[116:119]
	v_mfma_f32_16x16x32_bf16 v[112:115], v[174:177], v[186:189], v[112:115]
	v_mfma_f32_16x16x32_bf16 v[100:103], v[166:169], v[194:197], v[100:103]
	v_mfma_f32_16x16x32_bf16 v[96:99], v[174:177], v[194:197], v[96:99]
	v_mfma_f32_16x16x32_bf16 v[84:87], v[166:169], v[210:213], v[84:87]
	v_mfma_f32_16x16x32_bf16 v[80:83], v[174:177], v[210:213], v[80:83]
	v_mfma_f32_16x16x32_bf16 v[68:71], v[166:169], v[218:221], v[68:71]
	v_mfma_f32_16x16x32_bf16 v[64:67], v[174:177], v[218:221], v[64:67]
	s_setprio 0
	s_barrier
	s_mov_b64 s[2:3], s[50:51]
	ds_read_b128 v[178:181], v206 offset:16384
	ds_read_b128 v[186:189], v206 offset:17408
	ds_read_b128 v[190:193], v206 offset:18432
	ds_read_b128 v[194:197], v206 offset:19456
	ds_read_b128 v[198:201], v206 offset:20480
	ds_read_b128 v[210:213], v206 offset:21504
	ds_read_b128 v[214:217], v206 offset:22528
	s_mov_b32 m0, s75
	ds_read_b128 v[218:221], v206 offset:23552
	global_load_lds_dwordx4 v146, s[2:3]
	s_add_i32 m0, s75, 0x2000
	s_add_i32 s75, s67, s33
	global_load_lds_dwordx4 v150, s[2:3]
	s_add_u32 s2, s50, 0x20000
	s_addc_u32 s3, s51, 0
	s_mov_b32 m0, s75
	s_add_i32 s76, 0, 0x1c000
	global_load_lds_dwordx4 v146, s[2:3]
	s_add_i32 m0, s75, 0x2000
	s_add_i32 s75, 0, 0x18000
	global_load_lds_dwordx4 v150, s[2:3]
	s_mov_b32 m0, s45
	s_mov_b64 s[2:3], s[52:53]
	global_load_lds_dwordx4 v144, s[2:3]
	s_mov_b32 m0, s47
	s_add_i32 s74, s74, 2
	global_load_lds_dwordx4 v148, s[2:3]
	s_waitcnt vmcnt(8) lgkmcnt(0)
	s_barrier
	s_setprio 1
	v_mfma_f32_16x16x32_bf16 v[60:63], v[128:131], v[178:181], v[60:63]
	v_mfma_f32_16x16x32_bf16 v[56:59], v[136:139], v[178:181], v[56:59]
	v_mfma_f32_16x16x32_bf16 v[44:47], v[128:131], v[190:193], v[44:47]
	v_mfma_f32_16x16x32_bf16 v[40:43], v[136:139], v[190:193], v[40:43]
	v_mfma_f32_16x16x32_bf16 v[28:31], v[128:131], v[198:201], v[28:31]
	v_mfma_f32_16x16x32_bf16 v[24:27], v[136:139], v[198:201], v[24:27]
	v_mfma_f32_16x16x32_bf16 v[12:15], v[128:131], v[214:217], v[12:15]
	v_mfma_f32_16x16x32_bf16 v[8:11], v[136:139], v[214:217], v[8:11]
	v_mfma_f32_16x16x32_bf16 v[60:63], v[132:135], v[186:189], v[60:63]
	v_mfma_f32_16x16x32_bf16 v[56:59], v[140:143], v[186:189], v[56:59]
	v_mfma_f32_16x16x32_bf16 v[44:47], v[132:135], v[194:197], v[44:47]
	v_mfma_f32_16x16x32_bf16 v[40:43], v[140:143], v[194:197], v[40:43]
	v_mfma_f32_16x16x32_bf16 v[28:31], v[132:135], v[210:213], v[28:31]
	v_mfma_f32_16x16x32_bf16 v[24:27], v[140:143], v[210:213], v[24:27]
	v_mfma_f32_16x16x32_bf16 v[12:15], v[132:135], v[218:221], v[12:15]
	v_mfma_f32_16x16x32_bf16 v[8:11], v[140:143], v[218:221], v[8:11]
	v_mfma_f32_16x16x32_bf16 v[52:55], v[162:165], v[178:181], v[52:55]
	v_mfma_f32_16x16x32_bf16 v[48:51], v[170:173], v[178:181], v[48:51]
	v_mfma_f32_16x16x32_bf16 v[36:39], v[162:165], v[190:193], v[36:39]
	v_mfma_f32_16x16x32_bf16 v[32:35], v[170:173], v[190:193], v[32:35]
	v_mfma_f32_16x16x32_bf16 v[20:23], v[162:165], v[198:201], v[20:23]
	v_mfma_f32_16x16x32_bf16 v[16:19], v[170:173], v[198:201], v[16:19]
	v_mfma_f32_16x16x32_bf16 v[4:7], v[162:165], v[214:217], v[4:7]
	v_mfma_f32_16x16x32_bf16 v[0:3], v[170:173], v[214:217], v[0:3]
	v_mfma_f32_16x16x32_bf16 v[52:55], v[166:169], v[186:189], v[52:55]
	v_mfma_f32_16x16x32_bf16 v[48:51], v[174:177], v[186:189], v[48:51]
	v_mfma_f32_16x16x32_bf16 v[36:39], v[166:169], v[194:197], v[36:39]
	v_mfma_f32_16x16x32_bf16 v[32:35], v[174:177], v[194:197], v[32:35]
	v_mfma_f32_16x16x32_bf16 v[20:23], v[166:169], v[210:213], v[20:23]
	v_mfma_f32_16x16x32_bf16 v[16:19], v[174:177], v[210:213], v[16:19]
	v_mfma_f32_16x16x32_bf16 v[4:7], v[166:169], v[218:221], v[4:7]
	v_mfma_f32_16x16x32_bf16 v[0:3], v[174:177], v[218:221], v[0:3]
	s_setprio 0
	s_barrier
; #define PG8_STAGE(bufoff, gbase, voff) do { unsigned long long _gb = (unsigned long long)(gbase); asm volatile("" : "+s"(_gb)); _Pragma("unroll") for (int _i = 0; _i < 2; ++_i) \
;         __builtin_amdgcn_global_load_lds((const GAS unsigned*)((const GAS char*)_gb + (voff)[_i]), (LAS unsigned*)(lds + (bufoff) + ldsw + _i * 8192), 16, 0, 0); } while (0)
; #define PG8_LDA(dst, b, h) do { _Pragma("unroll") for (int m = 0; m < 4; ++m) _Pragma("unroll") for (int k = 0; k < 2; ++k) dst[m][k] = *(const LAS bf16x8*)(lds + PG8_SA(b, h) + aoff + m * 2048 + k * 1024); } while (0)
; #define PG8_LDB(dst, b, h) do { _Pragma("unroll") for (int n = 0; n < 2; ++n) _Pragma("unroll") for (int k = 0; k < 2; ++k) dst[n][k] = *(const LAS bf16x8*)(lds + PG8_SB(b, h) + boff + n * 2048 + k * 1024); } while (0)
; #define PG8_MMA(ai, bj, At, Bt) do { __builtin_amdgcn_s_setprio(1); _Pragma("unroll") for (int m = 0; m < 4; ++m) _Pragma("unroll") for (int n = 0; n < 2; ++n) _Pragma("unroll") for (int k = 0; k < 2; ++k) \
;         acc[ai][bj][m][n] = __builtin_amdgcn_mfma_f32_16x16x32_bf16(Bt[n][k], At[m][k], acc[ai][bj][m][n], 0, 0, 0); __builtin_amdgcn_s_setprio(0); } while (0)
; #define PG8_WAIT_V(n) asm volatile("s_waitcnt vmcnt(" #n ")" ::: "memory")
; #define PG8_WAIT_L(n) asm volatile("s_waitcnt lgkmcnt(" #n ")" ::: "memory")
; #define PG8_BAR __builtin_amdgcn_s_barrier()
; #define PG8_SCHED __builtin_amdgcn_sched_barrier(0)
; template <class Epi, bool ALIGN_EPI>
; __device__ __forceinline__ void gemm_phase(LAS unsigned char* lds, const Gemm g, const StaticOrder& S, const Epi& E, const int wid) {
;     ...
;             PG8_LDB(B0, 1, 0); PG8_LDB(B1, 1, 1); PG8_SCHED; PG8_LDA(At, 1, 0); PG8_STAGE(PG8_SA(0, 1), a2 + hstep, voffA);
;             PG8_WAIT_V(8); PG8_WAIT_L(0); PG8_BAR; PG8_MMA(0, 0, At, B0); PG8_MMA(0, 1, At, B1); PG8_BAR; PG8_SCHED;
;             PG8_LDA(At, 1, 1); PG8_STAGE(PG8_SB(1, 0), b3, voffB); PG8_STAGE(PG8_SB(1, 1), b3 + hstepB, voffB); PG8_STAGE(PG8_SA(1, 0), a3, voffA);
;             PG8_WAIT_V(8); PG8_WAIT_L(0); PG8_BAR; PG8_MMA(1, 0, At, B0); PG8_MMA(1, 1, At, B1); PG8_BAR; PG8_SCHED;
;         }
;         if constexpr (ALIGN_EPI) { if (wr == 0) PG8_BAR; }
	v_add_u32_e32 v140, s75, v203
	v_add_u32_e32 v152, s76, v203
	ds_read_b128 v[128:131], v140
	ds_read_b128 v[132:135], v140 offset:1024
	ds_read_b128 v[136:139], v140 offset:2048
	ds_read_b128 v[140:143], v140 offset:3072
	ds_read_b128 v[162:165], v152
	ds_read_b128 v[166:169], v152 offset:1024
	ds_read_b128 v[170:173], v152 offset:2048
	ds_read_b128 v[174:177], v152 offset:3072
	s_add_u32 s2, s52, 0x80000
	s_addc_u32 s3, s53, 0
	s_mov_b32 m0, s57
	ds_read_b128 v[178:181], v206 offset:32768
	ds_read_b128 v[186:189], v206 offset:33792
	ds_read_b128 v[190:193], v206 offset:34816
	ds_read_b128 v[194:197], v206 offset:35840
	ds_read_b128 v[198:201], v206 offset:36864
	ds_read_b128 v[210:213], v206 offset:37888
	ds_read_b128 v[214:217], v206 offset:38912
	ds_read_b128 v[218:221], v206 offset:39936
	global_load_lds_dwordx4 v144, s[2:3]
	s_mov_b32 m0, s58
	s_add_i32 s52, s75, s33
	global_load_lds_dwordx4 v148, s[2:3]
	s_waitcnt vmcnt(8) lgkmcnt(0)
	s_barrier
	s_setprio 1
	v_mfma_f32_16x16x32_bf16 v[124:127], v[128:131], v[178:181], v[124:127]
	v_mfma_f32_16x16x32_bf16 v[120:123], v[136:139], v[178:181], v[120:123]
	v_mfma_f32_16x16x32_bf16 v[108:111], v[128:131], v[190:193], v[108:111]
	v_mfma_f32_16x16x32_bf16 v[104:107], v[136:139], v[190:193], v[104:107]
	v_mfma_f32_16x16x32_bf16 v[92:95], v[128:131], v[198:201], v[92:95]
	v_mfma_f32_16x16x32_bf16 v[88:91], v[136:139], v[198:201], v[88:91]
	v_mfma_f32_16x16x32_bf16 v[76:79], v[128:131], v[214:217], v[76:79]
	v_mfma_f32_16x16x32_bf16 v[72:75], v[136:139], v[214:217], v[72:75]
	v_mfma_f32_16x16x32_bf16 v[124:127], v[132:135], v[186:189], v[124:127]
	v_mfma_f32_16x16x32_bf16 v[120:123], v[140:143], v[186:189], v[120:123]
	v_mfma_f32_16x16x32_bf16 v[108:111], v[132:135], v[194:197], v[108:111]
	v_mfma_f32_16x16x32_bf16 v[104:107], v[140:143], v[194:197], v[104:107]
	v_mfma_f32_16x16x32_bf16 v[92:95], v[132:135], v[210:213], v[92:95]
	v_mfma_f32_16x16x32_bf16 v[88:91], v[140:143], v[210:213], v[88:91]
	v_mfma_f32_16x16x32_bf16 v[76:79], v[132:135], v[218:221], v[76:79]
	v_mfma_f32_16x16x32_bf16 v[72:75], v[140:143], v[218:221], v[72:75]
	v_mfma_f32_16x16x32_bf16 v[116:119], v[162:165], v[178:181], v[116:119]
	v_mfma_f32_16x16x32_bf16 v[112:115], v[170:173], v[178:181], v[112:115]
	v_mfma_f32_16x16x32_bf16 v[100:103], v[162:165], v[190:193], v[100:103]
	v_mfma_f32_16x16x32_bf16 v[96:99], v[170:173], v[190:193], v[96:99]
	v_mfma_f32_16x16x32_bf16 v[84:87], v[162:165], v[198:201], v[84:87]
	v_mfma_f32_16x16x32_bf16 v[80:83], v[170:173], v[198:201], v[80:83]
	v_mfma_f32_16x16x32_bf16 v[68:71], v[162:165], v[214:217], v[68:71]
	v_mfma_f32_16x16x32_bf16 v[64:67], v[170:173], v[214:217], v[64:67]
	v_mfma_f32_16x16x32_bf16 v[116:119], v[166:169], v[186:189], v[116:119]
	v_mfma_f32_16x16x32_bf16 v[112:115], v[174:177], v[186:189], v[112:115]
	v_mfma_f32_16x16x32_bf16 v[100:103], v[166:169], v[194:197], v[100:103]
	v_mfma_f32_16x16x32_bf16 v[96:99], v[174:177], v[194:197], v[96:99]
	v_mfma_f32_16x16x32_bf16 v[84:87], v[166:169], v[210:213], v[84:87]
	v_mfma_f32_16x16x32_bf16 v[80:83], v[174:177], v[210:213], v[80:83]
	v_mfma_f32_16x16x32_bf16 v[68:71], v[166:169], v[218:221], v[68:71]
	v_mfma_f32_16x16x32_bf16 v[64:67], v[174:177], v[218:221], v[64:67]
	s_setprio 0
	s_barrier
	s_add_u32 s2, s50, 0x80
	s_addc_u32 s3, s51, 0
	ds_read_b128 v[178:181], v206 offset:49152
	ds_read_b128 v[186:189], v206 offset:50176
	ds_read_b128 v[190:193], v206 offset:51200
	ds_read_b128 v[194:197], v206 offset:52224
	ds_read_b128 v[198:201], v206 offset:53248
	ds_read_b128 v[210:213], v206 offset:54272
	ds_read_b128 v[214:217], v206 offset:55296
	s_mov_b32 m0, s52
	ds_read_b128 v[218:221], v206 offset:56320
	global_load_lds_dwordx4 v146, s[2:3]
	s_add_i32 m0, s52, 0x2000
	s_add_u32 s72, s72, 0x100
	s_addc_u32 s73, s73, 0
	global_load_lds_dwordx4 v150, s[2:3]
	s_add_u32 s2, s50, 0x20080
	s_addc_u32 s3, s51, 0
	s_add_i32 s50, s76, s33
	s_mov_b32 m0, s50
	s_nop 0
	global_load_lds_dwordx4 v146, s[2:3]
	s_add_i32 m0, s50, 0x2000
	s_nop 0
	global_load_lds_dwordx4 v150, s[2:3]
	s_mov_b32 m0, s63
	s_mov_b64 s[2:3], s[6:7]
	global_load_lds_dwordx4 v144, s[48:49]
	s_mov_b32 m0, s64
	s_nop 0
	global_load_lds_dwordx4 v148, s[48:49]
	s_waitcnt vmcnt(8) lgkmcnt(0)
	s_barrier
	s_setprio 1
	v_mfma_f32_16x16x32_bf16 v[60:63], v[128:131], v[178:181], v[60:63]
	v_mfma_f32_16x16x32_bf16 v[56:59], v[136:139], v[178:181], v[56:59]
	v_mfma_f32_16x16x32_bf16 v[44:47], v[128:131], v[190:193], v[44:47]
	v_mfma_f32_16x16x32_bf16 v[40:43], v[136:139], v[190:193], v[40:43]
	v_mfma_f32_16x16x32_bf16 v[28:31], v[128:131], v[198:201], v[28:31]
	v_mfma_f32_16x16x32_bf16 v[24:27], v[136:139], v[198:201], v[24:27]
	v_mfma_f32_16x16x32_bf16 v[12:15], v[128:131], v[214:217], v[12:15]
	v_mfma_f32_16x16x32_bf16 v[8:11], v[136:139], v[214:217], v[8:11]
	v_mfma_f32_16x16x32_bf16 v[60:63], v[132:135], v[186:189], v[60:63]
	v_mfma_f32_16x16x32_bf16 v[56:59], v[140:143], v[186:189], v[56:59]
	v_mfma_f32_16x16x32_bf16 v[44:47], v[132:135], v[194:197], v[44:47]
	v_mfma_f32_16x16x32_bf16 v[40:43], v[140:143], v[194:197], v[40:43]
	v_mfma_f32_16x16x32_bf16 v[28:31], v[132:135], v[210:213], v[28:31]
	v_mfma_f32_16x16x32_bf16 v[24:27], v[140:143], v[210:213], v[24:27]
	v_mfma_f32_16x16x32_bf16 v[12:15], v[132:135], v[218:221], v[12:15]
	v_mfma_f32_16x16x32_bf16 v[8:11], v[140:143], v[218:221], v[8:11]
	v_mfma_f32_16x16x32_bf16 v[52:55], v[162:165], v[178:181], v[52:55]
	v_mfma_f32_16x16x32_bf16 v[48:51], v[170:173], v[178:181], v[48:51]
	v_mfma_f32_16x16x32_bf16 v[36:39], v[162:165], v[190:193], v[36:39]
	v_mfma_f32_16x16x32_bf16 v[32:35], v[170:173], v[190:193], v[32:35]
	v_mfma_f32_16x16x32_bf16 v[20:23], v[162:165], v[198:201], v[20:23]
	v_mfma_f32_16x16x32_bf16 v[16:19], v[170:173], v[198:201], v[16:19]
	v_mfma_f32_16x16x32_bf16 v[4:7], v[162:165], v[214:217], v[4:7]
	v_mfma_f32_16x16x32_bf16 v[0:3], v[170:173], v[214:217], v[0:3]
	v_mfma_f32_16x16x32_bf16 v[52:55], v[166:169], v[186:189], v[52:55]
	v_mfma_f32_16x16x32_bf16 v[48:51], v[174:177], v[186:189], v[48:51]
	v_mfma_f32_16x16x32_bf16 v[36:39], v[166:169], v[194:197], v[36:39]
	v_mfma_f32_16x16x32_bf16 v[32:35], v[174:177], v[194:197], v[32:35]
	v_mfma_f32_16x16x32_bf16 v[20:23], v[166:169], v[210:213], v[20:23]
	v_mfma_f32_16x16x32_bf16 v[16:19], v[174:177], v[210:213], v[16:19]
	v_mfma_f32_16x16x32_bf16 v[4:7], v[166:169], v[218:221], v[4:7]
	v_mfma_f32_16x16x32_bf16 v[0:3], v[174:177], v[218:221], v[0:3]
	s_setprio 0
	s_barrier
	s_cmp_gt_u32 s74, 29
	s_cbranch_scc0 .LBB0_105
	s_and_b64 vcc, exec, s[84:85]
	s_cbranch_vccz .LBB0_108
	s_barrier

; #define PG8_STAGE(bufoff, gbase, voff) do { unsigned long long _gb = (unsigned long long)(gbase); asm volatile("" : "+s"(_gb)); _Pragma("unroll") for (int _i = 0; _i < 2; ++_i) \
;         __builtin_amdgcn_global_load_lds((const GAS unsigned*)((const GAS char*)_gb + (voff)[_i]), (LAS unsigned*)(lds + (bufoff) + ldsw + _i * 8192), 16, 0, 0); } while (0)
; #define PG8_LDA(dst, b, h) do { _Pragma("unroll") for (int m = 0; m < 4; ++m) _Pragma("unroll") for (int k = 0; k < 2; ++k) dst[m][k] = *(const LAS bf16x8*)(lds + PG8_SA(b, h) + aoff + m * 2048 + k * 1024); } while (0)
; #define PG8_LDB(dst, b, h) do { _Pragma("unroll") for (int n = 0; n < 2; ++n) _Pragma("unroll") for (int k = 0; k < 2; ++k) dst[n][k] = *(const LAS bf16x8*)(lds + PG8_SB(b, h) + boff + n * 2048 + k * 1024); } while (0)
; #define PG8_WAIT_V(n) asm volatile("s_waitcnt vmcnt(" #n ")" ::: "memory")
; #define PG8_BAR __builtin_amdgcn_s_barrier()
; template <class Epi, bool ALIGN_EPI>
; __device__ __forceinline__ void gemm_phase(LAS unsigned char* lds, const Gemm g, const StaticOrder& S, const Epi& E, const int wid) {
;     ...
;         const char* nA = has_next ? (const char*)g.A + (size_t)nxt.pm * tstep : cA; const char* nB = has_next ? (const char*)g.Bt + (size_t)nxt.pn * tstep : cB;
;         for (int t = 0; t < nt; t += 2) {
;             const bool last = (t == nt - 2);
;             const char* a1 = cA + (size_t)(t + 1) * kstep;
;             const char* a2 = last ? nA : cA + (size_t)(t + 2) * kstep; const char* b2 = last ? nB : cB + (size_t)(t + 2) * kstep;
;             const char* a3 = a2 + kstep; const char* b3 = b2 + kstep;
;             PG8_LDB(B0, 0, 0); PG8_LDB(B1, 0, 1); PG8_SCHED; PG8_LDA(At, 0, 0); PG8_STAGE(PG8_SA(1, 1), a1 + hstep, voffA);
;             PG8_WAIT_V(8); PG8_WAIT_L(0); PG8_BAR; PG8_MMA(0, 0, At, B0); PG8_MMA(0, 1, At, B1); PG8_BAR; PG8_SCHED;
;             PG8_LDA(At, 0, 1); PG8_STAGE(PG8_SB(0, 0), b2, voffB); PG8_STAGE(PG8_SB(0, 1), b2 + hstepB, voffB); PG8_STAGE(PG8_SA(0, 0), a2, voffA);
;             PG8_WAIT_V(8); PG8_WAIT_L(0); PG8_BAR; PG8_MMA(1, 0, At, B0); PG8_MMA(1, 1, At, B1); PG8_BAR; PG8_SCHED;
;             PG8_LDB(B0, 1, 0); PG8_LDB(B1, 1, 1); PG8_SCHED; PG8_LDA(At, 1, 0); PG8_STAGE(PG8_SA(0, 1), a2 + hstep, voffA);
;             PG8_WAIT_V(8); PG8_WAIT_L(0); PG8_BAR; PG8_MMA(0, 0, At, B0); PG8_MMA(0, 1, At, B1); PG8_BAR; PG8_SCHED;
.LBB0_722:
	ds_read_b128 v[128:131], v203
	ds_read_b128 v[132:135], v203 offset:1024
	ds_read_b128 v[136:139], v203 offset:2048
	ds_read_b128 v[140:143], v203 offset:3072
	ds_read_b128 v[144:147], v204
	ds_read_b128 v[148:151], v204 offset:1024
	ds_read_b128 v[152:155], v204 offset:2048
	ds_read_b128 v[156:159], v204 offset:3072
	s_cmp_eq_u32 s52, 28
	s_cselect_b32 s30, s21, s50
	s_cselect_b32 s31, s15, s51
	s_cselect_b32 s28, s47, s48
	s_cselect_b32 s29, s13, s49
	s_add_u32 s26, s30, 0x80
	s_addc_u32 s27, s31, 0
	s_mov_b64 s[54:55], s[24:25]
	ds_read_b128 v[160:163], v205
	ds_read_b128 v[164:167], v205 offset:1024
	ds_read_b128 v[168:171], v205 offset:2048
	ds_read_b128 v[172:175], v205 offset:3072
	ds_read_b128 v[188:191], v205 offset:4096
	ds_read_b128 v[192:195], v205 offset:5120
	ds_read_b128 v[196:199], v205 offset:6144
	s_add_i32 m0, s23, 0xc000
	ds_read_b128 v[206:209], v205 offset:7168
	global_load_lds_dwordx4 v176, s[54:55]
	s_add_i32 m0, s23, 0xe000
	s_add_i32 s53, s45, s33
	global_load_lds_dwordx4 v180, s[54:55]
	s_waitcnt vmcnt(8) lgkmcnt(0)
	s_barrier
	s_setprio 1
	v_mfma_f32_16x16x32_bf16 v[124:127], v[128:131], v[160:163], v[124:127]
	v_mfma_f32_16x16x32_bf16 v[120:123], v[136:139], v[160:163], v[120:123]
	v_mfma_f32_16x16x32_bf16 v[108:111], v[128:131], v[168:171], v[108:111]
	v_mfma_f32_16x16x32_bf16 v[104:107], v[136:139], v[168:171], v[104:107]
	v_mfma_f32_16x16x32_bf16 v[92:95], v[128:131], v[188:191], v[92:95]
	v_mfma_f32_16x16x32_bf16 v[88:91], v[136:139], v[188:191], v[88:91]
	v_mfma_f32_16x16x32_bf16 v[76:79], v[128:131], v[196:199], v[76:79]
	v_mfma_f32_16x16x32_bf16 v[72:75], v[136:139], v[196:199], v[72:75]
	v_mfma_f32_16x16x32_bf16 v[124:127], v[132:135], v[164:167], v[124:127]
	v_mfma_f32_16x16x32_bf16 v[120:123], v[140:143], v[164:167], v[120:123]
	v_mfma_f32_16x16x32_bf16 v[108:111], v[132:135], v[172:175], v[108:111]
	v_mfma_f32_16x16x32_bf16 v[104:107], v[140:143], v[172:175], v[104:107]
	v_mfma_f32_16x16x32_bf16 v[92:95], v[132:135], v[192:195], v[92:95]
	v_mfma_f32_16x16x32_bf16 v[88:91], v[140:143], v[192:195], v[88:91]
	v_mfma_f32_16x16x32_bf16 v[76:79], v[132:135], v[206:209], v[76:79]
	v_mfma_f32_16x16x32_bf16 v[72:75], v[140:143], v[206:209], v[72:75]
	v_mfma_f32_16x16x32_bf16 v[116:119], v[144:147], v[160:163], v[116:119]
	v_mfma_f32_16x16x32_bf16 v[112:115], v[152:155], v[160:163], v[112:115]
	v_mfma_f32_16x16x32_bf16 v[100:103], v[144:147], v[168:171], v[100:103]
	v_mfma_f32_16x16x32_bf16 v[96:99], v[152:155], v[168:171], v[96:99]
	v_mfma_f32_16x16x32_bf16 v[84:87], v[144:147], v[188:191], v[84:87]
	v_mfma_f32_16x16x32_bf16 v[80:83], v[152:155], v[188:191], v[80:83]
	v_mfma_f32_16x16x32_bf16 v[68:71], v[144:147], v[196:199], v[68:71]
	v_mfma_f32_16x16x32_bf16 v[64:67], v[152:155], v[196:199], v[64:67]
	v_mfma_f32_16x16x32_bf16 v[116:119], v[148:151], v[164:167], v[116:119]
	v_mfma_f32_16x16x32_bf16 v[112:115], v[156:159], v[164:167], v[112:115]
	v_mfma_f32_16x16x32_bf16 v[100:103], v[148:151], v[172:175], v[100:103]
	v_mfma_f32_16x16x32_bf16 v[96:99], v[156:159], v[172:175], v[96:99]
	v_mfma_f32_16x16x32_bf16 v[84:87], v[148:151], v[192:195], v[84:87]
	v_mfma_f32_16x16x32_bf16 v[80:83], v[156:159], v[192:195], v[80:83]
	v_mfma_f32_16x16x32_bf16 v[68:71], v[148:151], v[206:209], v[68:71]
	v_mfma_f32_16x16x32_bf16 v[64:67], v[156:159], v[206:209], v[64:67]
	s_setprio 0
	s_barrier
	s_mov_b64 s[54:55], s[28:29]
	ds_read_b128 v[160:163], v205 offset:16384
	ds_read_b128 v[164:167], v205 offset:17408
	ds_read_b128 v[168:171], v205 offset:18432
	ds_read_b128 v[172:175], v205 offset:19456
	ds_read_b128 v[188:191], v205 offset:20480
	ds_read_b128 v[192:195], v205 offset:21504
	ds_read_b128 v[196:199], v205 offset:22528
	s_mov_b32 m0, s53
	ds_read_b128 v[206:209], v205 offset:23552
	global_load_lds_dwordx4 v178, s[54:55]
	s_add_i32 m0, s53, 0x2000
	s_add_i32 s53, s46, s33
	global_load_lds_dwordx4 v182, s[54:55]
	s_add_u32 s54, s28, 0x20000
	s_addc_u32 s55, s29, 0
	s_mov_b32 m0, s53
	s_add_i32 s52, s52, 2
	global_load_lds_dwordx4 v178, s[54:55]
	s_add_i32 m0, s53, 0x2000
	s_add_i32 s53, 0, 0x18000
	global_load_lds_dwordx4 v182, s[54:55]
	s_mov_b32 m0, s23
	s_mov_b64 s[54:55], s[30:31]
	global_load_lds_dwordx4 v176, s[54:55]
	s_mov_b32 m0, s38
	s_add_u32 s30, s30, 0x80000
	s_addc_u32 s31, s31, 0
	global_load_lds_dwordx4 v180, s[54:55]
	s_waitcnt vmcnt(8) lgkmcnt(0)
	s_barrier
	s_setprio 1
	v_mfma_f32_16x16x32_bf16 v[60:63], v[128:131], v[160:163], v[60:63]
	v_mfma_f32_16x16x32_bf16 v[56:59], v[136:139], v[160:163], v[56:59]
	v_mfma_f32_16x16x32_bf16 v[44:47], v[128:131], v[168:171], v[44:47]
	v_mfma_f32_16x16x32_bf16 v[40:43], v[136:139], v[168:171], v[40:43]
	v_mfma_f32_16x16x32_bf16 v[28:31], v[128:131], v[188:191], v[28:31]
	v_mfma_f32_16x16x32_bf16 v[24:27], v[136:139], v[188:191], v[24:27]
	v_mfma_f32_16x16x32_bf16 v[12:15], v[128:131], v[196:199], v[12:15]
	v_mfma_f32_16x16x32_bf16 v[8:11], v[136:139], v[196:199], v[8:11]
	v_mfma_f32_16x16x32_bf16 v[60:63], v[132:135], v[164:167], v[60:63]
	v_mfma_f32_16x16x32_bf16 v[56:59], v[140:143], v[164:167], v[56:59]
	v_mfma_f32_16x16x32_bf16 v[44:47], v[132:135], v[172:175], v[44:47]
	v_mfma_f32_16x16x32_bf16 v[40:43], v[140:143], v[172:175], v[40:43]
	v_mfma_f32_16x16x32_bf16 v[28:31], v[132:135], v[192:195], v[28:31]
	v_mfma_f32_16x16x32_bf16 v[24:27], v[140:143], v[192:195], v[24:27]
	v_mfma_f32_16x16x32_bf16 v[12:15], v[132:135], v[206:209], v[12:15]
	v_mfma_f32_16x16x32_bf16 v[8:11], v[140:143], v[206:209], v[8:11]
	v_mfma_f32_16x16x32_bf16 v[52:55], v[144:147], v[160:163], v[52:55]
	v_mfma_f32_16x16x32_bf16 v[48:51], v[152:155], v[160:163], v[48:51]
	v_mfma_f32_16x16x32_bf16 v[36:39], v[144:147], v[168:171], v[36:39]
	v_mfma_f32_16x16x32_bf16 v[32:35], v[152:155], v[168:171], v[32:35]
	v_mfma_f32_16x16x32_bf16 v[20:23], v[144:147], v[188:191], v[20:23]
	v_mfma_f32_16x16x32_bf16 v[16:19], v[152:155], v[188:191], v[16:19]
	v_mfma_f32_16x16x32_bf16 v[4:7], v[144:147], v[196:199], v[4:7]
	v_mfma_f32_16x16x32_bf16 v[0:3], v[152:155], v[196:199], v[0:3]
	v_mfma_f32_16x16x32_bf16 v[52:55], v[148:151], v[164:167], v[52:55]
	v_mfma_f32_16x16x32_bf16 v[48:51], v[156:159], v[164:167], v[48:51]
	v_mfma_f32_16x16x32_bf16 v[36:39], v[148:151], v[172:175], v[36:39]
	v_mfma_f32_16x16x32_bf16 v[32:35], v[156:159], v[172:175], v[32:35]
	v_mfma_f32_16x16x32_bf16 v[20:23], v[148:151], v[192:195], v[20:23]
	v_mfma_f32_16x16x32_bf16 v[16:19], v[156:159], v[192:195], v[16:19]
	v_mfma_f32_16x16x32_bf16 v[4:7], v[148:151], v[206:209], v[4:7]
	v_mfma_f32_16x16x32_bf16 v[0:3], v[156:159], v[206:209], v[0:3]
	s_setprio 0
	s_barrier
; #define PG8_STAGE(bufoff, gbase, voff) do { unsigned long long _gb = (unsigned long long)(gbase); asm volatile("" : "+s"(_gb)); _Pragma("unroll") for (int _i = 0; _i < 2; ++_i) \
;         __builtin_amdgcn_global_load_lds((const GAS unsigned*)((const GAS char*)_gb + (voff)[_i]), (LAS unsigned*)(lds + (bufoff) + ldsw + _i * 8192), 16, 0, 0); } while (0)
; #define PG8_LDA(dst, b, h) do { _Pragma("unroll") for (int m = 0; m < 4; ++m) _Pragma("unroll") for (int k = 0; k < 2; ++k) dst[m][k] = *(const LAS bf16x8*)(lds + PG8_SA(b, h) + aoff + m * 2048 + k * 1024); } while (0)
; #define PG8_LDB(dst, b, h) do { _Pragma("unroll") for (int n = 0; n < 2; ++n) _Pragma("unroll") for (int k = 0; k < 2; ++k) dst[n][k] = *(const LAS bf16x8*)(lds + PG8_SB(b, h) + boff + n * 2048 + k * 1024); } while (0)
; #define PG8_MMA(ai, bj, At, Bt) do { __builtin_amdgcn_s_setprio(1); _Pragma("unroll") for (int m = 0; m < 4; ++m) _Pragma("unroll") for (int n = 0; n < 2; ++n) _Pragma("unroll") for (int k = 0; k < 2; ++k) \
;         acc[ai][bj][m][n] = __builtin_amdgcn_mfma_f32_16x16x32_bf16(Bt[n][k], At[m][k], acc[ai][bj][m][n], 0, 0, 0); __builtin_amdgcn_s_setprio(0); } while (0)
; #define PG8_WAIT_V(n) asm volatile("s_waitcnt vmcnt(" #n ")" ::: "memory")
; #define PG8_WAIT_L(n) asm volatile("s_waitcnt lgkmcnt(" #n ")" ::: "memory")
; #define PG8_BAR __builtin_amdgcn_s_barrier()
; #define PG8_SCHED __builtin_amdgcn_sched_barrier(0)
; template <class Epi, bool ALIGN_EPI>
; __device__ __forceinline__ void gemm_phase(LAS unsigned char* lds, const Gemm g, const StaticOrder& S, const Epi& E, const int wid) {
;     ...
;             PG8_LDB(B0, 1, 0); PG8_LDB(B1, 1, 1); PG8_SCHED; PG8_LDA(At, 1, 0); PG8_STAGE(PG8_SA(0, 1), a2 + hstep, voffA);
;             PG8_WAIT_V(8); PG8_WAIT_L(0); PG8_BAR; PG8_MMA(0, 0, At, B0); PG8_MMA(0, 1, At, B1); PG8_BAR; PG8_SCHED;
;             PG8_LDA(At, 1, 1); PG8_STAGE(PG8_SB(1, 0), b3, voffB); PG8_STAGE(PG8_SB(1, 1), b3 + hstepB, voffB); PG8_STAGE(PG8_SA(1, 0), a3, voffA);
;             PG8_WAIT_V(8); PG8_WAIT_L(0); PG8_BAR; PG8_MMA(1, 0, At, B0); PG8_MMA(1, 1, At, B1); PG8_BAR; PG8_SCHED;
	s_add_i32 s54, 0, 0x1c000
	v_add_u32_e32 v140, s53, v201
	v_add_u32_e32 v156, s54, v201
	ds_read_b128 v[128:131], v140
	ds_read_b128 v[132:135], v140 offset:1024
	ds_read_b128 v[136:139], v140 offset:2048
	ds_read_b128 v[140:143], v140 offset:3072
	ds_read_b128 v[144:147], v156
	ds_read_b128 v[148:151], v156 offset:1024
	ds_read_b128 v[152:155], v156 offset:2048
	ds_read_b128 v[156:159], v156 offset:3072
	s_mov_b32 m0, s39
	ds_read_b128 v[160:163], v205 offset:32768
	ds_read_b128 v[164:167], v205 offset:33792
	ds_read_b128 v[168:171], v205 offset:34816
	ds_read_b128 v[172:175], v205 offset:35840
	ds_read_b128 v[188:191], v205 offset:36864
	ds_read_b128 v[192:195], v205 offset:37888
	ds_read_b128 v[196:199], v205 offset:38912
	ds_read_b128 v[206:209], v205 offset:39936
	global_load_lds_dwordx4 v176, s[30:31]
	s_mov_b32 m0, s40
	s_add_i32 s53, s53, s33
	global_load_lds_dwordx4 v180, s[30:31]
	s_waitcnt vmcnt(8) lgkmcnt(0)
	s_barrier
	s_setprio 1
	v_mfma_f32_16x16x32_bf16 v[124:127], v[128:131], v[160:163], v[124:127]
	v_mfma_f32_16x16x32_bf16 v[120:123], v[136:139], v[160:163], v[120:123]
	v_mfma_f32_16x16x32_bf16 v[108:111], v[128:131], v[168:171], v[108:111]
	v_mfma_f32_16x16x32_bf16 v[104:107], v[136:139], v[168:171], v[104:107]
	v_mfma_f32_16x16x32_bf16 v[92:95], v[128:131], v[188:191], v[92:95]
	v_mfma_f32_16x16x32_bf16 v[88:91], v[136:139], v[188:191], v[88:91]
	v_mfma_f32_16x16x32_bf16 v[76:79], v[128:131], v[196:199], v[76:79]
	v_mfma_f32_16x16x32_bf16 v[72:75], v[136:139], v[196:199], v[72:75]
	v_mfma_f32_16x16x32_bf16 v[124:127], v[132:135], v[164:167], v[124:127]
	v_mfma_f32_16x16x32_bf16 v[120:123], v[140:143], v[164:167], v[120:123]
	v_mfma_f32_16x16x32_bf16 v[108:111], v[132:135], v[172:175], v[108:111]
	v_mfma_f32_16x16x32_bf16 v[104:107], v[140:143], v[172:175], v[104:107]
	v_mfma_f32_16x16x32_bf16 v[92:95], v[132:135], v[192:195], v[92:95]
	v_mfma_f32_16x16x32_bf16 v[88:91], v[140:143], v[192:195], v[88:91]
	v_mfma_f32_16x16x32_bf16 v[76:79], v[132:135], v[206:209], v[76:79]
	v_mfma_f32_16x16x32_bf16 v[72:75], v[140:143], v[206:209], v[72:75]
	v_mfma_f32_16x16x32_bf16 v[116:119], v[144:147], v[160:163], v[116:119]
	v_mfma_f32_16x16x32_bf16 v[112:115], v[152:155], v[160:163], v[112:115]
	v_mfma_f32_16x16x32_bf16 v[100:103], v[144:147], v[168:171], v[100:103]
	v_mfma_f32_16x16x32_bf16 v[96:99], v[152:155], v[168:171], v[96:99]
	v_mfma_f32_16x16x32_bf16 v[84:87], v[144:147], v[188:191], v[84:87]
	v_mfma_f32_16x16x32_bf16 v[80:83], v[152:155], v[188:191], v[80:83]
	v_mfma_f32_16x16x32_bf16 v[68:71], v[144:147], v[196:199], v[68:71]
	v_mfma_f32_16x16x32_bf16 v[64:67], v[152:155], v[196:199], v[64:67]
	v_mfma_f32_16x16x32_bf16 v[116:119], v[148:151], v[164:167], v[116:119]
	v_mfma_f32_16x16x32_bf16 v[112:115], v[156:159], v[164:167], v[112:115]
	v_mfma_f32_16x16x32_bf16 v[100:103], v[148:151], v[172:175], v[100:103]
	v_mfma_f32_16x16x32_bf16 v[96:99], v[156:159], v[172:175], v[96:99]
	v_mfma_f32_16x16x32_bf16 v[84:87], v[148:151], v[192:195], v[84:87]
	v_mfma_f32_16x16x32_bf16 v[80:83], v[156:159], v[192:195], v[80:83]
	v_mfma_f32_16x16x32_bf16 v[68:71], v[148:151], v[206:209], v[68:71]
	v_mfma_f32_16x16x32_bf16 v[64:67], v[156:159], v[206:209], v[64:67]
	s_setprio 0
	s_barrier
	s_add_u32 s30, s28, 0x80
	s_addc_u32 s31, s29, 0
	ds_read_b128 v[160:163], v205 offset:49152
	ds_read_b128 v[164:167], v205 offset:50176
	ds_read_b128 v[168:171], v205 offset:51200
	ds_read_b128 v[172:175], v205 offset:52224
	ds_read_b128 v[188:191], v205 offset:53248
	ds_read_b128 v[192:195], v205 offset:54272
	ds_read_b128 v[196:199], v205 offset:55296
	s_mov_b32 m0, s53
	ds_read_b128 v[206:209], v205 offset:56320
	global_load_lds_dwordx4 v178, s[30:31]
	s_add_i32 m0, s53, 0x2000
	s_add_u32 s28, s28, 0x20080
	s_addc_u32 s29, s29, 0
	global_load_lds_dwordx4 v182, s[30:31]
	s_add_i32 s30, s54, s33
	s_mov_b32 m0, s30
	s_add_u32 s48, s48, 0x100
	s_addc_u32 s49, s49, 0
	global_load_lds_dwordx4 v178, s[28:29]
	s_add_i32 m0, s30, 0x2000
	s_add_u32 s24, s24, 0x100
	s_addc_u32 s25, s25, 0
	global_load_lds_dwordx4 v182, s[28:29]
	s_mov_b32 m0, s42
	s_add_u32 s50, s50, 0x100
	s_addc_u32 s51, s51, 0
	global_load_lds_dwordx4 v176, s[26:27]
	s_mov_b32 m0, s43
	s_nop 0
	global_load_lds_dwordx4 v180, s[26:27]
	s_waitcnt vmcnt(8) lgkmcnt(0)
	s_barrier
	s_setprio 1
	v_mfma_f32_16x16x32_bf16 v[60:63], v[128:131], v[160:163], v[60:63]
	v_mfma_f32_16x16x32_bf16 v[56:59], v[136:139], v[160:163], v[56:59]
	v_mfma_f32_16x16x32_bf16 v[44:47], v[128:131], v[168:171], v[44:47]
	v_mfma_f32_16x16x32_bf16 v[40:43], v[136:139], v[168:171], v[40:43]
	v_mfma_f32_16x16x32_bf16 v[28:31], v[128:131], v[188:191], v[28:31]
	v_mfma_f32_16x16x32_bf16 v[24:27], v[136:139], v[188:191], v[24:27]
	v_mfma_f32_16x16x32_bf16 v[12:15], v[128:131], v[196:199], v[12:15]
	v_mfma_f32_16x16x32_bf16 v[8:11], v[136:139], v[196:199], v[8:11]
	v_mfma_f32_16x16x32_bf16 v[60:63], v[132:135], v[164:167], v[60:63]
	v_mfma_f32_16x16x32_bf16 v[56:59], v[140:143], v[164:167], v[56:59]
	v_mfma_f32_16x16x32_bf16 v[44:47], v[132:135], v[172:175], v[44:47]
	v_mfma_f32_16x16x32_bf16 v[40:43], v[140:143], v[172:175], v[40:43]
	v_mfma_f32_16x16x32_bf16 v[28:31], v[132:135], v[192:195], v[28:31]
	v_mfma_f32_16x16x32_bf16 v[24:27], v[140:143], v[192:195], v[24:27]
	v_mfma_f32_16x16x32_bf16 v[12:15], v[132:135], v[206:209], v[12:15]
	v_mfma_f32_16x16x32_bf16 v[8:11], v[140:143], v[206:209], v[8:11]
	v_mfma_f32_16x16x32_bf16 v[52:55], v[144:147], v[160:163], v[52:55]
	v_mfma_f32_16x16x32_bf16 v[48:51], v[152:155], v[160:163], v[48:51]
	v_mfma_f32_16x16x32_bf16 v[36:39], v[144:147], v[168:171], v[36:39]
	v_mfma_f32_16x16x32_bf16 v[32:35], v[152:155], v[168:171], v[32:35]
	v_mfma_f32_16x16x32_bf16 v[20:23], v[144:147], v[188:191], v[20:23]
	v_mfma_f32_16x16x32_bf16 v[16:19], v[152:155], v[188:191], v[16:19]
	v_mfma_f32_16x16x32_bf16 v[4:7], v[144:147], v[196:199], v[4:7]
	v_mfma_f32_16x16x32_bf16 v[0:3], v[152:155], v[196:199], v[0:3]
	v_mfma_f32_16x16x32_bf16 v[52:55], v[148:151], v[164:167], v[52:55]
	v_mfma_f32_16x16x32_bf16 v[48:51], v[156:159], v[164:167], v[48:51]
	v_mfma_f32_16x16x32_bf16 v[36:39], v[148:151], v[172:175], v[36:39]
	v_mfma_f32_16x16x32_bf16 v[32:35], v[156:159], v[172:175], v[32:35]
	v_mfma_f32_16x16x32_bf16 v[20:23], v[148:151], v[192:195], v[20:23]
	v_mfma_f32_16x16x32_bf16 v[16:19], v[156:159], v[192:195], v[16:19]
	v_mfma_f32_16x16x32_bf16 v[4:7], v[148:151], v[206:209], v[4:7]
	v_mfma_f32_16x16x32_bf16 v[0:3], v[156:159], v[206:209], v[0:3]
	s_setprio 0
	s_barrier
	s_cmp_gt_u32 s52, 29
	s_cbranch_scc0 .LBB0_722
	s_and_b64 vcc, exec, s[84:85]
	s_cbranch_vccz .LBB0_725
	s_barrier

; #define PG8_STAGE(bufoff, gbase, voff) do { unsigned long long _gb = (unsigned long long)(gbase); asm volatile("" : "+s"(_gb)); _Pragma("unroll") for (int _i = 0; _i < 2; ++_i) \
;         __builtin_amdgcn_global_load_lds((const GAS unsigned*)((const GAS char*)_gb + (voff)[_i]), (LAS unsigned*)(lds + (bufoff) + ldsw + _i * 8192), 16, 0, 0); } while (0)
; #define PG8_LDA(dst, b, h) do { _Pragma("unroll") for (int m = 0; m < 4; ++m) _Pragma("unroll") for (int k = 0; k < 2; ++k) dst[m][k] = *(const LAS bf16x8*)(lds + PG8_SA(b, h) + aoff + m * 2048 + k * 1024); } while (0)
; #define PG8_LDB(dst, b, h) do { _Pragma("unroll") for (int n = 0; n < 2; ++n) _Pragma("unroll") for (int k = 0; k < 2; ++k) dst[n][k] = *(const LAS bf16x8*)(lds + PG8_SB(b, h) + boff + n * 2048 + k * 1024); } while (0)
; #define PG8_MMA(ai, bj, At, Bt) do { __builtin_amdgcn_s_setprio(1); _Pragma("unroll") for (int m = 0; m < 4; ++m) _Pragma("unroll") for (int n = 0; n < 2; ++n) _Pragma("unroll") for (int k = 0; k < 2; ++k) \
;         acc[ai][bj][m][n] = __builtin_amdgcn_mfma_f32_16x16x32_bf16(Bt[n][k], At[m][k], acc[ai][bj][m][n], 0, 0, 0); __builtin_amdgcn_s_setprio(0); } while (0)
; #define PG8_WAIT_V(n) asm volatile("s_waitcnt vmcnt(" #n ")" ::: "memory")
; #define PG8_WAIT_L(n) asm volatile("s_waitcnt lgkmcnt(" #n ")" ::: "memory")
; #define PG8_BAR __builtin_amdgcn_s_barrier()
; template <class Epi, bool ALIGN_EPI>
; __device__ __forceinline__ void gemm_phase(LAS unsigned char* lds, const Gemm g, const StaticOrder& S, const Epi& E, const int wid) {
;     ...
;             const bool last = (t == nt - 2);
;             const char* a1 = cA + (size_t)(t + 1) * kstep;
;             const char* a2 = last ? nA : cA + (size_t)(t + 2) * kstep; const char* b2 = last ? nB : cB + (size_t)(t + 2) * kstep;
;             const char* a3 = a2 + kstep; const char* b3 = b2 + kstep;
;             PG8_LDB(B0, 0, 0); PG8_LDB(B1, 0, 1); PG8_SCHED; PG8_LDA(At, 0, 0); PG8_STAGE(PG8_SA(1, 1), a1 + hstep, voffA);
;             PG8_WAIT_V(8); PG8_WAIT_L(0); PG8_BAR; PG8_MMA(0, 0, At, B0); PG8_MMA(0, 1, At, B1); PG8_BAR; PG8_SCHED;
;             PG8_LDA(At, 0, 1); PG8_STAGE(PG8_SB(0, 0), b2, voffB); PG8_STAGE(PG8_SB(0, 1), b2 + hstepB, voffB); PG8_STAGE(PG8_SA(0, 0), a2, voffA);
;             PG8_WAIT_V(8); PG8_WAIT_L(0); PG8_BAR; PG8_MMA(1, 0, At, B0); PG8_MMA(1, 1, At, B1); PG8_BAR; PG8_SCHED;
.LBB0_811:
	ds_read_b128 v[128:131], v202
	ds_read_b128 v[132:135], v202 offset:1024
	ds_read_b128 v[136:139], v202 offset:2048
	ds_read_b128 v[140:143], v202 offset:3072
	ds_read_b128 v[144:147], v203
	ds_read_b128 v[148:151], v203 offset:1024
	ds_read_b128 v[152:155], v203 offset:2048
	ds_read_b128 v[156:159], v203 offset:3072
	s_cmp_eq_u32 s49, 28
	s_cselect_b32 s24, s43, s47
	s_cselect_b32 s25, s13, s48
	s_cselect_b32 s22, s44, s45
	s_cselect_b32 s23, s11, s46
	s_add_u32 s20, s24, 0x80
	s_addc_u32 s21, s25, 0
	s_mov_b64 s[50:51], s[18:19]
	ds_read_b128 v[160:163], v204
	ds_read_b128 v[164:167], v204 offset:1024
	ds_read_b128 v[168:171], v204 offset:2048
	ds_read_b128 v[172:175], v204 offset:3072
	ds_read_b128 v[188:191], v204 offset:4096
	ds_read_b128 v[192:195], v204 offset:5120
	ds_read_b128 v[196:199], v204 offset:6144
	s_add_i32 m0, s28, 0xc000
	ds_read_b128 v[206:209], v204 offset:7168
	global_load_lds_dwordx4 v182, s[50:51]
	s_add_i32 m0, s28, 0xe000
	s_add_i32 s52, s38, s33
	global_load_lds_dwordx4 v178, s[50:51]
	s_waitcnt vmcnt(8) lgkmcnt(0)
	s_barrier
	s_setprio 1
	v_mfma_f32_16x16x32_bf16 v[124:127], v[128:131], v[160:163], v[124:127]
	v_mfma_f32_16x16x32_bf16 v[120:123], v[136:139], v[160:163], v[120:123]
	v_mfma_f32_16x16x32_bf16 v[108:111], v[128:131], v[168:171], v[108:111]
	v_mfma_f32_16x16x32_bf16 v[104:107], v[136:139], v[168:171], v[104:107]
	v_mfma_f32_16x16x32_bf16 v[92:95], v[128:131], v[188:191], v[92:95]
	v_mfma_f32_16x16x32_bf16 v[88:91], v[136:139], v[188:191], v[88:91]
	v_mfma_f32_16x16x32_bf16 v[76:79], v[128:131], v[196:199], v[76:79]
	v_mfma_f32_16x16x32_bf16 v[72:75], v[136:139], v[196:199], v[72:75]
	v_mfma_f32_16x16x32_bf16 v[124:127], v[132:135], v[164:167], v[124:127]
	v_mfma_f32_16x16x32_bf16 v[120:123], v[140:143], v[164:167], v[120:123]
	v_mfma_f32_16x16x32_bf16 v[108:111], v[132:135], v[172:175], v[108:111]
	v_mfma_f32_16x16x32_bf16 v[104:107], v[140:143], v[172:175], v[104:107]
	v_mfma_f32_16x16x32_bf16 v[92:95], v[132:135], v[192:195], v[92:95]
	v_mfma_f32_16x16x32_bf16 v[88:91], v[140:143], v[192:195], v[88:91]
	v_mfma_f32_16x16x32_bf16 v[76:79], v[132:135], v[206:209], v[76:79]
	v_mfma_f32_16x16x32_bf16 v[72:75], v[140:143], v[206:209], v[72:75]
	v_mfma_f32_16x16x32_bf16 v[116:119], v[144:147], v[160:163], v[116:119]
	v_mfma_f32_16x16x32_bf16 v[112:115], v[152:155], v[160:163], v[112:115]
	v_mfma_f32_16x16x32_bf16 v[100:103], v[144:147], v[168:171], v[100:103]
	v_mfma_f32_16x16x32_bf16 v[96:99], v[152:155], v[168:171], v[96:99]
	v_mfma_f32_16x16x32_bf16 v[84:87], v[144:147], v[188:191], v[84:87]
	v_mfma_f32_16x16x32_bf16 v[80:83], v[152:155], v[188:191], v[80:83]
	v_mfma_f32_16x16x32_bf16 v[68:71], v[144:147], v[196:199], v[68:71]
	v_mfma_f32_16x16x32_bf16 v[64:67], v[152:155], v[196:199], v[64:67]
	v_mfma_f32_16x16x32_bf16 v[116:119], v[148:151], v[164:167], v[116:119]
	v_mfma_f32_16x16x32_bf16 v[112:115], v[156:159], v[164:167], v[112:115]
	v_mfma_f32_16x16x32_bf16 v[100:103], v[148:151], v[172:175], v[100:103]
	v_mfma_f32_16x16x32_bf16 v[96:99], v[156:159], v[172:175], v[96:99]
	v_mfma_f32_16x16x32_bf16 v[84:87], v[148:151], v[192:195], v[84:87]
	v_mfma_f32_16x16x32_bf16 v[80:83], v[156:159], v[192:195], v[80:83]
	v_mfma_f32_16x16x32_bf16 v[68:71], v[148:151], v[206:209], v[68:71]
	v_mfma_f32_16x16x32_bf16 v[64:67], v[156:159], v[206:209], v[64:67]
	s_setprio 0
	s_barrier
	s_mov_b64 s[50:51], s[22:23]
	ds_read_b128 v[160:163], v204 offset:16384
	ds_read_b128 v[164:167], v204 offset:17408
	ds_read_b128 v[168:171], v204 offset:18432
	ds_read_b128 v[172:175], v204 offset:19456
	ds_read_b128 v[188:191], v204 offset:20480
	ds_read_b128 v[192:195], v204 offset:21504
	ds_read_b128 v[196:199], v204 offset:22528
	s_mov_b32 m0, s52
	ds_read_b128 v[206:209], v204 offset:23552
	global_load_lds_dwordx4 v180, s[50:51]
	s_add_i32 m0, s52, 0x2000
	s_add_i32 s52, s39, s33
	global_load_lds_dwordx4 v176, s[50:51]
	s_add_u32 s50, s22, 0x20000
	s_addc_u32 s51, s23, 0
	s_mov_b32 m0, s52
	s_add_i32 s49, s49, 2
	global_load_lds_dwordx4 v180, s[50:51]
	s_add_i32 m0, s52, 0x2000
	s_add_u32 s45, s45, 0x100
	s_addc_u32 s46, s46, 0
	global_load_lds_dwordx4 v176, s[50:51]
	s_mov_b32 m0, s28
	s_mov_b64 s[50:51], s[24:25]
	global_load_lds_dwordx4 v182, s[50:51]
	s_mov_b32 m0, s29
	s_add_u32 s24, s24, 0x80000
	s_addc_u32 s25, s25, 0
	global_load_lds_dwordx4 v178, s[50:51]
	s_waitcnt vmcnt(8) lgkmcnt(0)
	s_barrier
	s_setprio 1
	v_mfma_f32_16x16x32_bf16 v[60:63], v[128:131], v[160:163], v[60:63]
	v_mfma_f32_16x16x32_bf16 v[56:59], v[136:139], v[160:163], v[56:59]
	v_mfma_f32_16x16x32_bf16 v[44:47], v[128:131], v[168:171], v[44:47]
	v_mfma_f32_16x16x32_bf16 v[40:43], v[136:139], v[168:171], v[40:43]
	v_mfma_f32_16x16x32_bf16 v[28:31], v[128:131], v[188:191], v[28:31]
	v_mfma_f32_16x16x32_bf16 v[24:27], v[136:139], v[188:191], v[24:27]
	v_mfma_f32_16x16x32_bf16 v[12:15], v[128:131], v[196:199], v[12:15]
	v_mfma_f32_16x16x32_bf16 v[8:11], v[136:139], v[196:199], v[8:11]
	v_mfma_f32_16x16x32_bf16 v[60:63], v[132:135], v[164:167], v[60:63]
	v_mfma_f32_16x16x32_bf16 v[56:59], v[140:143], v[164:167], v[56:59]
	v_mfma_f32_16x16x32_bf16 v[44:47], v[132:135], v[172:175], v[44:47]
	v_mfma_f32_16x16x32_bf16 v[40:43], v[140:143], v[172:175], v[40:43]
	v_mfma_f32_16x16x32_bf16 v[28:31], v[132:135], v[192:195], v[28:31]
	v_mfma_f32_16x16x32_bf16 v[24:27], v[140:143], v[192:195], v[24:27]
	v_mfma_f32_16x16x32_bf16 v[12:15], v[132:135], v[206:209], v[12:15]
	v_mfma_f32_16x16x32_bf16 v[8:11], v[140:143], v[206:209], v[8:11]
	v_mfma_f32_16x16x32_bf16 v[52:55], v[144:147], v[160:163], v[52:55]
	v_mfma_f32_16x16x32_bf16 v[48:51], v[152:155], v[160:163], v[48:51]
	v_mfma_f32_16x16x32_bf16 v[36:39], v[144:147], v[168:171], v[36:39]
	v_mfma_f32_16x16x32_bf16 v[32:35], v[152:155], v[168:171], v[32:35]
	v_mfma_f32_16x16x32_bf16 v[20:23], v[144:147], v[188:191], v[20:23]
	v_mfma_f32_16x16x32_bf16 v[16:19], v[152:155], v[188:191], v[16:19]
	v_mfma_f32_16x16x32_bf16 v[4:7], v[144:147], v[196:199], v[4:7]
	v_mfma_f32_16x16x32_bf16 v[0:3], v[152:155], v[196:199], v[0:3]
	v_mfma_f32_16x16x32_bf16 v[52:55], v[148:151], v[164:167], v[52:55]
	v_mfma_f32_16x16x32_bf16 v[48:51], v[156:159], v[164:167], v[48:51]
	v_mfma_f32_16x16x32_bf16 v[36:39], v[148:151], v[172:175], v[36:39]
	v_mfma_f32_16x16x32_bf16 v[32:35], v[156:159], v[172:175], v[32:35]
	v_mfma_f32_16x16x32_bf16 v[20:23], v[148:151], v[192:195], v[20:23]
	v_mfma_f32_16x16x32_bf16 v[16:19], v[156:159], v[192:195], v[16:19]
	v_mfma_f32_16x16x32_bf16 v[4:7], v[148:151], v[206:209], v[4:7]
	v_mfma_f32_16x16x32_bf16 v[0:3], v[156:159], v[206:209], v[0:3]
	s_setprio 0
	s_barrier
; #define PG8_STAGE(bufoff, gbase, voff) do { unsigned long long _gb = (unsigned long long)(gbase); asm volatile("" : "+s"(_gb)); _Pragma("unroll") for (int _i = 0; _i < 2; ++_i) \
;         __builtin_amdgcn_global_load_lds((const GAS unsigned*)((const GAS char*)_gb + (voff)[_i]), (LAS unsigned*)(lds + (bufoff) + ldsw + _i * 8192), 16, 0, 0); } while (0)
; #define PG8_LDA(dst, b, h) do { _Pragma("unroll") for (int m = 0; m < 4; ++m) _Pragma("unroll") for (int k = 0; k < 2; ++k) dst[m][k] = *(const LAS bf16x8*)(lds + PG8_SA(b, h) + aoff + m * 2048 + k * 1024); } while (0)
; #define PG8_LDB(dst, b, h) do { _Pragma("unroll") for (int n = 0; n < 2; ++n) _Pragma("unroll") for (int k = 0; k < 2; ++k) dst[n][k] = *(const LAS bf16x8*)(lds + PG8_SB(b, h) + boff + n * 2048 + k * 1024); } while (0)
; #define PG8_MMA(ai, bj, At, Bt) do { __builtin_amdgcn_s_setprio(1); _Pragma("unroll") for (int m = 0; m < 4; ++m) _Pragma("unroll") for (int n = 0; n < 2; ++n) _Pragma("unroll") for (int k = 0; k < 2; ++k) \
;         acc[ai][bj][m][n] = __builtin_amdgcn_mfma_f32_16x16x32_bf16(Bt[n][k], At[m][k], acc[ai][bj][m][n], 0, 0, 0); __builtin_amdgcn_s_setprio(0); } while (0)
; #define PG8_WAIT_V(n) asm volatile("s_waitcnt vmcnt(" #n ")" ::: "memory")
; #define PG8_WAIT_L(n) asm volatile("s_waitcnt lgkmcnt(" #n ")" ::: "memory")
; #define PG8_BAR __builtin_amdgcn_s_barrier()
; #define PG8_SCHED __builtin_amdgcn_sched_barrier(0)
; template <class Epi, bool ALIGN_EPI>
; __device__ __forceinline__ void gemm_phase(LAS unsigned char* lds, const Gemm g, const StaticOrder& S, const Epi& E, const int wid) {
;     ...
;             PG8_LDB(B0, 1, 0); PG8_LDB(B1, 1, 1); PG8_SCHED; PG8_LDA(At, 1, 0); PG8_STAGE(PG8_SA(0, 1), a2 + hstep, voffA);
;             PG8_WAIT_V(8); PG8_WAIT_L(0); PG8_BAR; PG8_MMA(0, 0, At, B0); PG8_MMA(0, 1, At, B1); PG8_BAR; PG8_SCHED;
;             PG8_LDA(At, 1, 1); PG8_STAGE(PG8_SB(1, 0), b3, voffB); PG8_STAGE(PG8_SB(1, 1), b3 + hstepB, voffB); PG8_STAGE(PG8_SA(1, 0), a3, voffA);
;             PG8_WAIT_V(8); PG8_WAIT_L(0); PG8_BAR; PG8_MMA(1, 0, At, B0); PG8_MMA(1, 1, At, B1); PG8_BAR; PG8_SCHED;
	s_add_i32 s50, 0, 0x18000
	s_add_i32 s51, 0, 0x1c000
	v_add_u32_e32 v140, s50, v201
	v_add_u32_e32 v156, s51, v201
	ds_read_b128 v[128:131], v140
	ds_read_b128 v[132:135], v140 offset:1024
	ds_read_b128 v[136:139], v140 offset:2048
	ds_read_b128 v[140:143], v140 offset:3072
	ds_read_b128 v[144:147], v156
	ds_read_b128 v[148:151], v156 offset:1024
	ds_read_b128 v[152:155], v156 offset:2048
	ds_read_b128 v[156:159], v156 offset:3072
	s_mov_b32 m0, s30
	ds_read_b128 v[160:163], v204 offset:32768
	ds_read_b128 v[164:167], v204 offset:33792
	ds_read_b128 v[168:171], v204 offset:34816
	ds_read_b128 v[172:175], v204 offset:35840
	ds_read_b128 v[188:191], v204 offset:36864
	ds_read_b128 v[192:195], v204 offset:37888
	ds_read_b128 v[196:199], v204 offset:38912
	ds_read_b128 v[206:209], v204 offset:39936
	global_load_lds_dwordx4 v182, s[24:25]
	s_mov_b32 m0, s31
	s_add_i32 s50, s50, s33
	global_load_lds_dwordx4 v178, s[24:25]
	s_waitcnt vmcnt(8) lgkmcnt(0)
	s_barrier
	s_setprio 1
	v_mfma_f32_16x16x32_bf16 v[124:127], v[128:131], v[160:163], v[124:127]
	v_mfma_f32_16x16x32_bf16 v[120:123], v[136:139], v[160:163], v[120:123]
	v_mfma_f32_16x16x32_bf16 v[108:111], v[128:131], v[168:171], v[108:111]
	v_mfma_f32_16x16x32_bf16 v[104:107], v[136:139], v[168:171], v[104:107]
	v_mfma_f32_16x16x32_bf16 v[92:95], v[128:131], v[188:191], v[92:95]
	v_mfma_f32_16x16x32_bf16 v[88:91], v[136:139], v[188:191], v[88:91]
	v_mfma_f32_16x16x32_bf16 v[76:79], v[128:131], v[196:199], v[76:79]
	v_mfma_f32_16x16x32_bf16 v[72:75], v[136:139], v[196:199], v[72:75]
	v_mfma_f32_16x16x32_bf16 v[124:127], v[132:135], v[164:167], v[124:127]
	v_mfma_f32_16x16x32_bf16 v[120:123], v[140:143], v[164:167], v[120:123]
	v_mfma_f32_16x16x32_bf16 v[108:111], v[132:135], v[172:175], v[108:111]
	v_mfma_f32_16x16x32_bf16 v[104:107], v[140:143], v[172:175], v[104:107]
	v_mfma_f32_16x16x32_bf16 v[92:95], v[132:135], v[192:195], v[92:95]
	v_mfma_f32_16x16x32_bf16 v[88:91], v[140:143], v[192:195], v[88:91]
	v_mfma_f32_16x16x32_bf16 v[76:79], v[132:135], v[206:209], v[76:79]
	v_mfma_f32_16x16x32_bf16 v[72:75], v[140:143], v[206:209], v[72:75]
	v_mfma_f32_16x16x32_bf16 v[116:119], v[144:147], v[160:163], v[116:119]
	v_mfma_f32_16x16x32_bf16 v[112:115], v[152:155], v[160:163], v[112:115]
	v_mfma_f32_16x16x32_bf16 v[100:103], v[144:147], v[168:171], v[100:103]
	v_mfma_f32_16x16x32_bf16 v[96:99], v[152:155], v[168:171], v[96:99]
	v_mfma_f32_16x16x32_bf16 v[84:87], v[144:147], v[188:191], v[84:87]
	v_mfma_f32_16x16x32_bf16 v[80:83], v[152:155], v[188:191], v[80:83]
	v_mfma_f32_16x16x32_bf16 v[68:71], v[144:147], v[196:199], v[68:71]
	v_mfma_f32_16x16x32_bf16 v[64:67], v[152:155], v[196:199], v[64:67]
	v_mfma_f32_16x16x32_bf16 v[116:119], v[148:151], v[164:167], v[116:119]
	v_mfma_f32_16x16x32_bf16 v[112:115], v[156:159], v[164:167], v[112:115]
	v_mfma_f32_16x16x32_bf16 v[100:103], v[148:151], v[172:175], v[100:103]
	v_mfma_f32_16x16x32_bf16 v[96:99], v[156:159], v[172:175], v[96:99]
	v_mfma_f32_16x16x32_bf16 v[84:87], v[148:151], v[192:195], v[84:87]
	v_mfma_f32_16x16x32_bf16 v[80:83], v[156:159], v[192:195], v[80:83]
	v_mfma_f32_16x16x32_bf16 v[68:71], v[148:151], v[206:209], v[68:71]
	v_mfma_f32_16x16x32_bf16 v[64:67], v[156:159], v[206:209], v[64:67]
	s_setprio 0
	s_barrier
	s_add_u32 s24, s22, 0x80
	s_addc_u32 s25, s23, 0
	ds_read_b128 v[160:163], v204 offset:49152
	ds_read_b128 v[164:167], v204 offset:50176
	ds_read_b128 v[168:171], v204 offset:51200
	ds_read_b128 v[172:175], v204 offset:52224
	ds_read_b128 v[188:191], v204 offset:53248
	ds_read_b128 v[192:195], v204 offset:54272
	ds_read_b128 v[196:199], v204 offset:55296
	s_mov_b32 m0, s50
	ds_read_b128 v[206:209], v204 offset:56320
	global_load_lds_dwordx4 v180, s[24:25]
	s_add_i32 m0, s50, 0x2000
	s_add_u32 s22, s22, 0x20080
	s_addc_u32 s23, s23, 0
	global_load_lds_dwordx4 v176, s[24:25]
	s_add_i32 s24, s51, s33
	s_mov_b32 m0, s24
	s_add_u32 s18, s18, 0x100
	s_addc_u32 s19, s19, 0
	global_load_lds_dwordx4 v180, s[22:23]
	s_add_i32 m0, s24, 0x2000
	s_add_u32 s47, s47, 0x100
	s_addc_u32 s48, s48, 0
	global_load_lds_dwordx4 v176, s[22:23]
	s_mov_b32 m0, s34
	s_nop 0
	global_load_lds_dwordx4 v182, s[20:21]
	s_mov_b32 m0, s35
	s_nop 0
	global_load_lds_dwordx4 v178, s[20:21]
	s_waitcnt vmcnt(8) lgkmcnt(0)
	s_barrier
	s_setprio 1
	v_mfma_f32_16x16x32_bf16 v[60:63], v[128:131], v[160:163], v[60:63]
	v_mfma_f32_16x16x32_bf16 v[56:59], v[136:139], v[160:163], v[56:59]
	v_mfma_f32_16x16x32_bf16 v[44:47], v[128:131], v[168:171], v[44:47]
	v_mfma_f32_16x16x32_bf16 v[40:43], v[136:139], v[168:171], v[40:43]
	v_mfma_f32_16x16x32_bf16 v[28:31], v[128:131], v[188:191], v[28:31]
	v_mfma_f32_16x16x32_bf16 v[24:27], v[136:139], v[188:191], v[24:27]
	v_mfma_f32_16x16x32_bf16 v[12:15], v[128:131], v[196:199], v[12:15]
	v_mfma_f32_16x16x32_bf16 v[8:11], v[136:139], v[196:199], v[8:11]
	v_mfma_f32_16x16x32_bf16 v[60:63], v[132:135], v[164:167], v[60:63]
	v_mfma_f32_16x16x32_bf16 v[56:59], v[140:143], v[164:167], v[56:59]
	v_mfma_f32_16x16x32_bf16 v[44:47], v[132:135], v[172:175], v[44:47]
	v_mfma_f32_16x16x32_bf16 v[40:43], v[140:143], v[172:175], v[40:43]
	v_mfma_f32_16x16x32_bf16 v[28:31], v[132:135], v[192:195], v[28:31]
	v_mfma_f32_16x16x32_bf16 v[24:27], v[140:143], v[192:195], v[24:27]
	v_mfma_f32_16x16x32_bf16 v[12:15], v[132:135], v[206:209], v[12:15]
	v_mfma_f32_16x16x32_bf16 v[8:11], v[140:143], v[206:209], v[8:11]
	v_mfma_f32_16x16x32_bf16 v[52:55], v[144:147], v[160:163], v[52:55]
	v_mfma_f32_16x16x32_bf16 v[48:51], v[152:155], v[160:163], v[48:51]
	v_mfma_f32_16x16x32_bf16 v[36:39], v[144:147], v[168:171], v[36:39]
	v_mfma_f32_16x16x32_bf16 v[32:35], v[152:155], v[168:171], v[32:35]
	v_mfma_f32_16x16x32_bf16 v[20:23], v[144:147], v[188:191], v[20:23]
	v_mfma_f32_16x16x32_bf16 v[16:19], v[152:155], v[188:191], v[16:19]
	v_mfma_f32_16x16x32_bf16 v[4:7], v[144:147], v[196:199], v[4:7]
	v_mfma_f32_16x16x32_bf16 v[0:3], v[152:155], v[196:199], v[0:3]
	v_mfma_f32_16x16x32_bf16 v[52:55], v[148:151], v[164:167], v[52:55]
	v_mfma_f32_16x16x32_bf16 v[48:51], v[156:159], v[164:167], v[48:51]
	v_mfma_f32_16x16x32_bf16 v[36:39], v[148:151], v[172:175], v[36:39]
	v_mfma_f32_16x16x32_bf16 v[32:35], v[156:159], v[172:175], v[32:35]
	v_mfma_f32_16x16x32_bf16 v[20:23], v[148:151], v[192:195], v[20:23]
	v_mfma_f32_16x16x32_bf16 v[16:19], v[156:159], v[192:195], v[16:19]
	v_mfma_f32_16x16x32_bf16 v[4:7], v[148:151], v[206:209], v[4:7]
	v_mfma_f32_16x16x32_bf16 v[0:3], v[156:159], v[206:209], v[0:3]
	s_setprio 0
	s_barrier
	s_cmp_gt_u32 s49, 29
	s_cbranch_scc0 .LBB0_811
	s_and_b64 vcc, exec, s[84:85]
	s_cbranch_vccz .LBB0_814
	s_barrier
